# P3 attention second half-iteration rescheduled the same way (softmax VALU in the PV MFMA gaps)
# speedup vs baseline: 1.0107x; 1.0007x over previous
.LBB0_437:
	s_waitcnt lgkmcnt(0)
	s_barrier
	ds_read_b128 v[64:67], v166 offset:32768
	ds_read_b128 v[68:71], v166 offset:40960
	ds_read_b128 v[196:199], v167 offset:32768
	ds_read_b128 v[200:203], v167 offset:40960
	ds_read_b128 v[204:207], v168 offset:32768
	ds_read_b128 v[210:213], v168 offset:40960
	v_exp_f32_e32 v188, v188
	v_exp_f32_e32 v189, v189
	s_waitcnt lgkmcnt(5)
	v_mfma_f32_32x32x16_bf16 v[80:95], v[64:67], v[124:127], 0
	v_exp_f32_e32 v190, v190
	v_exp_f32_e32 v191, v191
	v_exp_f32_e32 v192, v192
	v_exp_f32_e32 v195, v181
	v_exp_f32_e32 v182, v182
	v_exp_f32_e32 v183, v183
	v_exp_f32_e32 v184, v184
	s_waitcnt lgkmcnt(4)
	v_mfma_f32_32x32x16_bf16 v[64:79], v[68:71], v[124:127], 0
	v_exp_f32_e32 v185, v185
	v_exp_f32_e32 v186, v186
	v_exp_f32_e32 v187, v187
	v_exp_f32_e32 v193, v193
	v_exp_f32_e32 v194, v194
	v_exp_f32_e32 v177, v177
	s_waitcnt lgkmcnt(3)
	v_mfma_f32_32x32x16_bf16 v[80:95], v[196:199], v[120:123], v[80:95]
	ds_read_b128 v[196:199], v169 offset:32768
	ds_read_b128 v[214:217], v169 offset:40960
	ds_read_b128 v[218:221], v170 offset:32768
	ds_read_b128 v[222:225], v170 offset:40960
	ds_read_b128 v[226:229], v171 offset:32768
	ds_read_b128 v[230:233], v171 offset:40960
	ds_read_b128 v[234:237], v172 offset:32768
	ds_read_b128 v[238:241], v172 offset:40960
	s_waitcnt lgkmcnt(10)
	v_mfma_f32_32x32x16_bf16 v[64:79], v[200:203], v[120:123], v[64:79]
	ds_read_b128 v[200:203], v173 offset:32768
	ds_read_b128 v[242:245], v173 offset:40960
	s_waitcnt lgkmcnt(11)
	v_mfma_f32_32x32x16_bf16 v[80:95], v[204:207], v[112:115], v[80:95]
	v_exp_f32_e32 v204, v180
	v_add_f32_e32 v180, v144, v143
	v_add_f32_e32 v180, v145, v180
	v_add_f32_e32 v180, v146, v180
	v_add_f32_e32 v180, v147, v180
	v_add_f32_e32 v180, v149, v180
	s_waitcnt lgkmcnt(10)
	v_mfma_f32_32x32x16_bf16 v[64:79], v[210:213], v[112:115], v[64:79]
	v_add_f32_e32 v180, v148, v180
	v_add_f32_e32 v180, v175, v180
	v_add_f32_e32 v180, v135, v180
	v_add_f32_e32 v180, v136, v180
	v_add_f32_e32 v180, v137, v180
	v_add_f32_e32 v180, v139, v180
	v_add_f32_e32 v180, v138, v180
	s_waitcnt lgkmcnt(9)
	v_mfma_f32_32x32x16_bf16 v[80:95], v[196:199], v[116:119], v[80:95]
	v_add_f32_e32 v180, v140, v180
	v_add_f32_e32 v180, v141, v180
	v_add_f32_e32 v180, v142, v180
	v_add_f32_e32 v180, v188, v180
	v_add_f32_e32 v180, v189, v180
	v_add_f32_e32 v180, v190, v180
	v_add_f32_e32 v180, v191, v180
	s_waitcnt lgkmcnt(8)
	v_mfma_f32_32x32x16_bf16 v[64:79], v[214:217], v[116:119], v[64:79]
	v_add_f32_e32 v180, v192, v180
	v_add_f32_e32 v180, v195, v180
	v_add_f32_e32 v180, v182, v180
	v_add_f32_e32 v180, v183, v180
	v_add_f32_e32 v180, v184, v180
	v_add_f32_e32 v180, v185, v180
	v_add_f32_e32 v180, v186, v180
	s_waitcnt lgkmcnt(7)
	v_mfma_f32_32x32x16_bf16 v[80:95], v[218:221], v[108:111], v[80:95]
	v_add_f32_e32 v180, v187, v180
	v_add_f32_e32 v180, v204, v180
	v_add_f32_e32 v180, v193, v180
	v_add_f32_e32 v180, v194, v180
	v_add_f32_e32 v180, v177, v180
	s_waitcnt lgkmcnt(6)
	v_mfma_f32_32x32x16_bf16 v[64:79], v[222:225], v[108:111], v[64:79]
	v_cvt_pk_bf16_f32 v144, v143, v144
	v_cvt_pk_bf16_f32 v145, v145, v146
	v_cvt_pk_bf16_f32 v146, v147, v149
	v_cvt_pk_bf16_f32 v147, v148, v175
	v_cvt_pk_bf16_f32 v136, v135, v136
	v_cvt_pk_bf16_f32 v137, v137, v139
	v_cvt_pk_bf16_f32 v138, v138, v140
	s_waitcnt lgkmcnt(5)
	v_mfma_f32_32x32x16_bf16 v[80:95], v[226:229], v[104:107], v[80:95]
	v_cvt_pk_bf16_f32 v139, v141, v142
	v_cvt_pk_bf16_f32 v140, v188, v189
	v_cvt_pk_bf16_f32 v141, v190, v191
	v_cvt_pk_bf16_f32 v142, v192, v195
	v_cvt_pk_bf16_f32 v143, v182, v183
	v_cvt_pk_bf16_f32 v182, v184, v185
	v_cvt_pk_bf16_f32 v183, v186, v187
	s_waitcnt lgkmcnt(4)
	v_mfma_f32_32x32x16_bf16 v[64:79], v[230:233], v[104:107], v[64:79]
	v_cvt_pk_bf16_f32 v184, v204, v193
	v_cvt_pk_bf16_f32 v185, v194, v177
	s_waitcnt lgkmcnt(3)
	v_mfma_f32_32x32x16_bf16 v[80:95], v[234:237], v[100:103], v[80:95]
	s_waitcnt lgkmcnt(2)
	v_mfma_f32_32x32x16_bf16 v[64:79], v[238:241], v[100:103], v[64:79]
	s_waitcnt lgkmcnt(1)
	v_mfma_f32_32x32x16_bf16 v[80:95], v[200:203], v[96:99], v[80:95]
	s_waitcnt lgkmcnt(0)
	v_mfma_f32_32x32x16_bf16 v[64:79], v[242:245], v[96:99], v[64:79]
	global_load_dwordx4 v[226:229], v132, s[28:29]
	global_load_dwordx4 v[230:233], v132, s[30:31]
	global_load_dwordx4 v[234:237], v133, s[28:29]
	global_load_dwordx4 v[238:241], v133, s[30:31]
	s_add_u32 s28, s28, 0x8000
	s_addc_u32 s29, s29, 0
	s_add_u32 s30, s30, 0x8000
	s_addc_u32 s31, s31, 0
	ds_read_b64_tr_b16 v[202:203], v160 offset:0
	ds_read_b64_tr_b16 v[204:205], v160 offset:0x800
	ds_read_b64_tr_b16 v[210:211], v160 offset:0x1000
	ds_read_b64_tr_b16 v[212:213], v160 offset:0x1800
	ds_read_b64_tr_b16 v[214:215], v160 offset:0x2000
	ds_read_b64_tr_b16 v[216:217], v160 offset:0x2800
	ds_read_b64_tr_b16 v[218:219], v160 offset:0x3000
	ds_read_b64_tr_b16 v[220:221], v160 offset:0x3800
	s_waitcnt lgkmcnt(0)
	s_nop 0
	v_mfma_f32_32x32x16_bf16 v[0:15], v[144:147], v[202:205], v[0:15]
	ds_read_b64_tr_b16 v[202:203], v160 offset:0x200
	ds_read_b64_tr_b16 v[204:205], v160 offset:0xa00
	v_max_f32_e32 v242, v80, v81
	v_max3_f32 v242, v242, v82, v83
	v_max3_f32 v242, v242, v84, v85
	v_max3_f32 v242, v242, v86, v87
	v_max3_f32 v242, v242, v88, v89
	v_mfma_f32_32x32x16_bf16 v[0:15], v[136:139], v[210:213], v[0:15]
	ds_read_b64_tr_b16 v[210:211], v160 offset:0x1200
	ds_read_b64_tr_b16 v[212:213], v160 offset:0x1a00
	v_max3_f32 v242, v242, v90, v91
	v_max3_f32 v242, v242, v92, v93
	v_max3_f32 v242, v242, v94, v95
	v_max3_f32 v242, v242, v64, v65
	v_max3_f32 v242, v242, v66, v67
	v_mfma_f32_32x32x16_bf16 v[0:15], v[140:143], v[214:217], v[0:15]
	ds_read_b64_tr_b16 v[214:215], v160 offset:0x2200
	ds_read_b64_tr_b16 v[216:217], v160 offset:0x2a00
	ds_read_b64_tr_b16 v[222:223], v160 offset:0x3200
	ds_read_b64_tr_b16 v[224:225], v160 offset:0x3a00
	v_max3_f32 v242, v242, v68, v69
	v_max3_f32 v242, v242, v70, v71
	v_max3_f32 v242, v242, v72, v73
	v_max3_f32 v242, v242, v74, v75
	v_max3_f32 v242, v242, v76, v77
	s_waitcnt lgkmcnt(0)
	v_mfma_f32_32x32x16_bf16 v[0:15], v[182:185], v[218:221], v[0:15]
	v_max3_f32 v242, v242, v78, v79
	v_mov_b32_e32 v243, v242
	v_mfma_f32_32x32x16_bf16 v[48:63], v[144:147], v[202:205], v[48:63]
	ds_read_b64_tr_b16 v[202:203], v160 offset:0x400
	ds_read_b64_tr_b16 v[204:205], v160 offset:0xc00
	v_permlane32_swap_b32_e32 v242, v243
	v_max_f32_e32 v242, v242, v243
	v_mfma_f32_32x32x16_bf16 v[48:63], v[136:139], v[210:213], v[48:63]
	ds_read_b64_tr_b16 v[210:211], v160 offset:0x1400
	ds_read_b64_tr_b16 v[212:213], v160 offset:0x1c00
	v_sub_f32_e32 v243, v242, v134
	v_max_f32_e32 v242, v134, v242
	v_sub_f32_e32 v148, v134, v242
	v_mul_f32_e32 v148, 0x3e0293ee, v148
	v_mfma_f32_32x32x16_bf16 v[48:63], v[140:143], v[214:217], v[48:63]
	ds_read_b64_tr_b16 v[214:215], v160 offset:0x2400
	ds_read_b64_tr_b16 v[216:217], v160 offset:0x2c00
	ds_read_b64_tr_b16 v[218:219], v160 offset:0x3400
	ds_read_b64_tr_b16 v[220:221], v160 offset:0x3c00
	v_exp_f32_e32 v148, v148
	v_cmp_ge_f32_e32 vcc, s15, v243
	s_cmp_eq_u64 vcc, exec
	s_cselect_b64 s[8:9], -1, 0
	s_waitcnt lgkmcnt(0)
	v_mfma_f32_32x32x16_bf16 v[48:63], v[182:185], v[222:225], v[48:63]
	v_cndmask_b32_e64 v177, v148, 1.0, s[8:9]
	v_cndmask_b32_e64 v175, v242, v134, s[8:9]
	v_mul_f32_e32 v244, 0xbe0293ee, v175
	v_pk_fma_f32 v[80:81], v[80:81], s[14:15], v[244:245] op_sel_hi:[1,0,0]
	v_pk_fma_f32 v[82:83], v[82:83], s[14:15], v[244:245] op_sel_hi:[1,0,0]
	v_mfma_f32_32x32x16_bf16 v[32:47], v[144:147], v[202:205], v[32:47]
	ds_read_b64_tr_b16 v[202:203], v160 offset:0x600
	ds_read_b64_tr_b16 v[204:205], v160 offset:0xe00
	v_pk_fma_f32 v[84:85], v[84:85], s[14:15], v[244:245] op_sel_hi:[1,0,0]
	v_pk_fma_f32 v[86:87], v[86:87], s[14:15], v[244:245] op_sel_hi:[1,0,0]
	v_pk_fma_f32 v[88:89], v[88:89], s[14:15], v[244:245] op_sel_hi:[1,0,0]
	v_pk_fma_f32 v[90:91], v[90:91], s[14:15], v[244:245] op_sel_hi:[1,0,0]
	v_mfma_f32_32x32x16_bf16 v[32:47], v[136:139], v[210:213], v[32:47]
	ds_read_b64_tr_b16 v[210:211], v160 offset:0x1600
	ds_read_b64_tr_b16 v[212:213], v160 offset:0x1e00
	v_pk_fma_f32 v[92:93], v[92:93], s[14:15], v[244:245] op_sel_hi:[1,0,0]
	v_pk_fma_f32 v[94:95], v[94:95], s[14:15], v[244:245] op_sel_hi:[1,0,0]
	v_pk_fma_f32 v[134:135], v[72:73], s[14:15], v[244:245] op_sel_hi:[1,0,0]
	v_pk_fma_f32 v[148:149], v[74:75], s[14:15], v[244:245] op_sel_hi:[1,0,0]
	v_mfma_f32_32x32x16_bf16 v[32:47], v[140:143], v[214:217], v[32:47]
	ds_read_b64_tr_b16 v[214:215], v160 offset:0x2600
	ds_read_b64_tr_b16 v[216:217], v160 offset:0x2e00
	ds_read_b64_tr_b16 v[222:223], v160 offset:0x3600
	ds_read_b64_tr_b16 v[224:225], v160 offset:0x3e00
	v_exp_f32_e32 v190, v80
	v_exp_f32_e32 v191, v81
	v_exp_f32_e32 v192, v82
	s_waitcnt lgkmcnt(0)
	v_mfma_f32_32x32x16_bf16 v[32:47], v[182:185], v[218:221], v[32:47]
	v_exp_f32_e32 v193, v83
	v_exp_f32_e32 v194, v84
	v_exp_f32_e32 v196, v85
	v_mfma_f32_32x32x16_bf16 v[16:31], v[144:147], v[202:205], v[16:31]
	v_pk_fma_f32 v[144:145], v[78:79], s[14:15], v[244:245] op_sel_hi:[1,0,0]
	v_pk_fma_f32 v[146:147], v[76:77], s[14:15], v[244:245] op_sel_hi:[1,0,0]
	v_exp_f32_e32 v195, v86
	v_exp_f32_e32 v197, v87
	v_mfma_f32_32x32x16_bf16 v[16:31], v[136:139], v[210:213], v[16:31]
	v_pk_fma_f32 v[136:137], v[70:71], s[14:15], v[244:245] op_sel_hi:[1,0,0]
	v_pk_fma_f32 v[138:139], v[68:69], s[14:15], v[244:245] op_sel_hi:[1,0,0]
	v_exp_f32_e32 v186, v91
	v_exp_f32_e32 v187, v93
	v_mfma_f32_32x32x16_bf16 v[16:31], v[140:143], v[214:217], v[16:31]
	v_pk_fma_f32 v[140:141], v[66:67], s[14:15], v[244:245] op_sel_hi:[1,0,0]
	v_pk_fma_f32 v[142:143], v[64:65], s[14:15], v[244:245] op_sel_hi:[1,0,0]
	v_exp_f32_e32 v188, v94
	v_exp_f32_e32 v189, v95
	v_mfma_f32_32x32x16_bf16 v[16:31], v[182:185], v[222:225], v[16:31]
	v_exp_f32_e32 v182, v88
	v_exp_f32_e32 v183, v89
	v_exp_f32_e32 v184, v90
	v_exp_f32_e32 v185, v92
	v_cmp_gt_f32_e32 vcc, 1.0, v177
	s_barrier
	s_waitcnt vmcnt(0)
	ds_write_b128 v164, v[226:229] offset:16384
	ds_write_b128 v165, v[234:237] offset:16384
	ds_write_b128 v162, v[230:233] offset:49152
	ds_write_b128 v163, v[238:241] offset:49152
	s_cbranch_vccz .LBB0_441
	s_and_saveexec_b64 s[2:3], s[6:7]
	ds_write_b32 v158, v177 offset:128
	s_or_b64 exec, exec, s[2:3]
	s_waitcnt lgkmcnt(0)
	v_add_u32_e32 v242, v131, v128
	ds_read_b128 v[226:229], v242 offset:224
	ds_read_b128 v[230:233], v242 offset:192
	ds_read_b128 v[234:237], v242 offset:160
	ds_read_b128 v[238:241], v242 offset:128
	s_waitcnt lgkmcnt(3)
	v_pk_mul_f32 v[12:13], v[12:13], v[226:227]
	s_waitcnt lgkmcnt(2)
	v_pk_mul_f32 v[8:9], v[8:9], v[230:231]
	s_waitcnt lgkmcnt(1)
	v_pk_mul_f32 v[4:5], v[4:5], v[234:235]
	v_pk_mul_f32 v[14:15], v[14:15], v[228:229]
	v_pk_mul_f32 v[10:11], v[10:11], v[232:233]
	v_pk_mul_f32 v[6:7], v[6:7], v[236:237]
	s_waitcnt lgkmcnt(0)
	v_pk_mul_f32 v[2:3], v[2:3], v[240:241]
	v_pk_mul_f32 v[0:1], v[0:1], v[238:239]
	v_pk_mul_f32 v[60:61], v[60:61], v[226:227]
	v_pk_mul_f32 v[56:57], v[56:57], v[230:231]
	v_pk_mul_f32 v[52:53], v[52:53], v[234:235]
	v_pk_mul_f32 v[62:63], v[62:63], v[228:229]
	v_pk_mul_f32 v[58:59], v[58:59], v[232:233]
	v_pk_mul_f32 v[54:55], v[54:55], v[236:237]
	v_pk_mul_f32 v[50:51], v[50:51], v[240:241]
	v_pk_mul_f32 v[48:49], v[48:49], v[238:239]
	v_pk_mul_f32 v[44:45], v[44:45], v[226:227]
	v_pk_mul_f32 v[40:41], v[40:41], v[230:231]
	v_pk_mul_f32 v[36:37], v[36:37], v[234:235]
	v_pk_mul_f32 v[46:47], v[46:47], v[228:229]
	v_pk_mul_f32 v[42:43], v[42:43], v[232:233]
	v_pk_mul_f32 v[38:39], v[38:39], v[236:237]
	v_pk_mul_f32 v[34:35], v[34:35], v[240:241]
	v_pk_mul_f32 v[32:33], v[32:33], v[238:239]
	v_pk_mul_f32 v[28:29], v[28:29], v[226:227]
	v_pk_mul_f32 v[24:25], v[24:25], v[230:231]
	v_pk_mul_f32 v[20:21], v[20:21], v[234:235]
	v_pk_mul_f32 v[30:31], v[30:31], v[228:229]
	v_pk_mul_f32 v[26:27], v[26:27], v[232:233]
	v_pk_mul_f32 v[22:23], v[22:23], v[236:237]
	v_pk_mul_f32 v[18:19], v[18:19], v[240:241]
	v_pk_mul_f32 v[16:17], v[16:17], v[238:239]
.LBB0_441:
	v_fma_f32 v64, v174, v159, v176
	s_add_i32 s68, s68, 2
	v_fma_f32 v159, v64, v179, v180
	s_cmp_gt_u32 s68, 32
	s_waitcnt lgkmcnt(0)
	s_barrier
	s_cbranch_scc1 .LBB0_443
	v_mov_b32_e32 v174, v177
	s_branch .LBB0_433
